# forgetting attention loop: early-exit votes read with two ds_read_b128 under one wait, ones vector hoisted out of the tile body
# speedup vs baseline: 1.0027x; 1.0014x over previous
; #define LAS __attribute__((address_space(3)))
; template <bool DIFF>
; __device__ __forceinline__ void attn_unit(CA& A, int l, int b, int hh, int qb, LAS unsigned char* lds, float lam, float lam_init) {
;     ...
;     if (!DIFF) {
;         if (tid == 0) { const unsigned* fl = (const unsigned*)(A.ws + WS_CTL) + 128 + l * 16 + b * 4 + hh; unsigned spins = 0;
;             while (__hip_atomic_load(fl, __ATOMIC_RELAXED, __HIP_MEMORY_SCOPE_AGENT) == 0u) { __builtin_amdgcn_s_sleep(2); if (++spins > (1u << 22)) break; } }
;         __syncthreads();
;     }
;     float ncq = 0.f;
;     if (!DIFF) { if (tid < 64) ncv = ncp[(NT - 1) * 64 + tid]; ncq = ncp[q0 + wq + r32]; }
;     ATT_WRITE(0);
;     __syncthreads();
;     f32x16 o[2], ol; float m_ref = 0.f;
; #pragma unroll
;     for (int r = 0; r < 16; ++r) { o[0][r] = 0.f; o[1][r] = 0.f; ol[r] = 0.f; }
;     f32x16 negm;
; #pragma unroll
;     for (int r = 0; r < 16; ++r) negm[r] = 0.f;
;     const bf16x8 ones = {0x3F80, 0x3F80, 0x3F80, 0x3F80, 0x3F80, 0x3F80, 0x3F80, 0x3F80};
;     const int qfirst = q0 + wq, qlast = qfirst + 31, qmine = qfirst + r32;
;     const int koff = DIFF ? strm * 32 : 0;
;     if (DIFF) {
;         m_ref = qkb;
; #pragma unroll
;         for (int r = 0; r < 16; ++r) negm[r] = -qkb;
;     } else {
;         m_ref = qkb + ncq;
;     }
;     volatile LAS int* votes = (volatile LAS int*)(lds + LDS_MAIN + 64);
;     bool first = true;
.LBB0_768:
	s_or_b64 exec, exec, s[6:7]
	v_lshl_add_u64 v[10:11], v[120:121], 2, s[10:11]
	global_load_dword v126, v[10:11], off
	s_movk_i32 s6, 0x90
	v_mul_lo_u32 v5, v5, s6
	s_mul_i32 s6, s15, 0x440
	v_add3_u32 v121, 0, v5, v2
	s_add_i32 s6, s6, 0
	v_lshlrev_b32_e32 v2, 2, v138
	v_lshl_add_u32 v140, v4, 1, s6
	v_add_u32_e32 v141, 0, v2
	s_waitcnt vmcnt(2)
	ds_write_b128 v121, v[112:115]
	s_waitcnt vmcnt(1)
	ds_write_b16 v140, v116 offset:18432
	ds_write_b16_d16_hi v140, v116 offset:18568
	ds_write_b16 v140, v117 offset:18704
	ds_write_b16_d16_hi v140, v117 offset:18840
	ds_write_b16 v140, v118 offset:18976
	ds_write_b16_d16_hi v140, v118 offset:19112
	ds_write_b16 v140, v119 offset:19248
	ds_write_b16_d16_hi v140, v119 offset:19384
	s_and_saveexec_b64 s[6:7], s[4:5]
	ds_write_b32 v141, v139 offset:35840
	s_or_b64 exec, exec, s[6:7]
	v_add_f32_e32 v2, v6, v7
	s_mov_b32 s6, 0xf800000
	v_mul_f32_e32 v5, 0x4f800000, v2
	v_cmp_gt_f32_e32 vcc, s6, v2
	v_max_f32_e32 v6, v8, v8
	v_max_f32_e32 v3, v3, v3
	v_cndmask_b32_e32 v2, v2, v5, vcc
	v_sqrt_f32_e32 v5, v2
	v_max_f32_e32 v3, v3, v6
	v_add_u32_e32 v144, 0, v9
	s_lshl_b32 s13, s15, 2
	v_add_u32_e32 v6, -1, v5
	v_fma_f32 v7, -v6, v5, v2
	v_cmp_ge_f32_e64 s[6:7], 0, v7
	v_add_u32_e32 v7, 1, v5
	v_mov_b32_e32 v14, v0
	v_cndmask_b32_e64 v6, v5, v6, s[6:7]
	v_fma_f32 v5, -v7, v5, v2
	v_cmp_lt_f32_e64 s[6:7], 0, v5
	v_mov_b32_e32 v15, v0
	s_add_i32 s30, s13, 0
	v_cndmask_b32_e64 v5, v6, v7, s[6:7]
	v_mul_f32_e32 v6, 0x37800000, v5
	v_cndmask_b32_e32 v5, v5, v6, vcc
	v_cmp_class_f32_e32 vcc, v2, v219
	v_cmp_eq_u32_e64 s[6:7], 0, v4
	v_add_u32_e32 v145, v144, v9
	v_cndmask_b32_e32 v2, v5, v2, vcc
	v_mul_f32_e32 v2, 0x41000000, v2
	v_mul_f32_e32 v2, v3, v2
	v_mul_f32_e32 v143, 0x3f828f5c, v2
	s_waitcnt vmcnt(0)
	v_fmac_f32_e32 v126, 0x3f828f5c, v2
	v_lshlrev_b32_e32 v142, 2, v1
	s_lshl_b32 s12, s12, 8
	v_mov_b32_e32 v1, v0
	v_mov_b32_e32 v2, v0
	v_mov_b32_e32 v3, v0
	v_mov_b32_e32 v4, v0
	v_mov_b32_e32 v5, v0
	v_mov_b32_e32 v6, v0
	v_mov_b32_e32 v7, v0
	v_mov_b32_e32 v8, v0
	v_mov_b32_e32 v9, v0
	v_mov_b32_e32 v10, v0
	v_mov_b32_e32 v11, v0
	v_mov_b32_e32 v12, v0
	v_mov_b32_e32 v13, v0
	v_mov_b64_e32 v[46:47], v[14:15]
	v_mov_b64_e32 v[30:31], v[14:15]
	v_mov_b64_e32 v[62:63], v[14:15]
	s_or_b32 s29, s26, 31
	s_mov_b32 s37, 0
	s_add_i32 s30, s30, 0x20040
	v_add_f32_e32 v146, v143, v143
	v_mul_u32_u24_e32 v147, 0x90, v137
	v_mul_u32_u24_e32 v148, 0x88, v137
	v_mov_b32_e32 v127, v126
	s_add_i32 s31, s27, -2
	s_sub_i32 s34, 0xfff, s12
	s_mov_b64 s[14:15], -1
	v_mov_b64_e32 v[44:45], v[12:13]
	v_mov_b64_e32 v[42:43], v[10:11]
	v_mov_b64_e32 v[40:41], v[8:9]
	v_mov_b64_e32 v[38:39], v[6:7]
	v_mov_b64_e32 v[36:37], v[4:5]
	v_mov_b64_e32 v[34:35], v[2:3]
	v_mov_b64_e32 v[32:33], v[0:1]
	v_mov_b64_e32 v[28:29], v[12:13]
	v_mov_b64_e32 v[26:27], v[10:11]
	v_mov_b64_e32 v[24:25], v[8:9]
	v_mov_b64_e32 v[22:23], v[6:7]
	v_mov_b64_e32 v[20:21], v[4:5]
	v_mov_b64_e32 v[18:19], v[2:3]
	v_mov_b64_e32 v[16:17], v[0:1]
	v_mov_b64_e32 v[60:61], v[12:13]
	v_mov_b64_e32 v[58:59], v[10:11]
	v_mov_b64_e32 v[56:57], v[8:9]
	v_mov_b64_e32 v[54:55], v[6:7]
	v_mov_b64_e32 v[52:53], v[4:5]
	v_mov_b64_e32 v[50:51], v[2:3]
	v_mov_b64_e32 v[48:49], v[0:1]
	v_mov_b32_e32 v204, s36
	v_mov_b32_e32 v205, s36
	v_mov_b32_e32 v206, s36
	v_mov_b32_e32 v207, s36
	s_waitcnt lgkmcnt(0)
	s_barrier
	s_branch .LBB0_773

; template <bool DIFF>
; __device__ __forceinline__ void attn_unit(CA& A, int l, int b, int hh, int qb, LAS unsigned char* lds, float lam, float lam_init) {
;     ...
;         if (has_next) ATT_WRITE(buf ^ 1);
;         if (!DIFF) {
;             const int vote = (!first && !__any(nc_hi + qkb - m_ref + 2.0f * qkb >= -48.0f)) ? 1 : 0;
;             if (lane == 0) votes[(tt & 1) * 8 + wid] = vote;
;         }
;         __syncthreads();
;         if (!has_next) break;
;         if (!DIFF) {
;             const int pb_ = (tt & 1) * 8;
;             const int all = votes[pb_] & votes[pb_ + 1] & votes[pb_ + 2] & votes[pb_ + 3] & votes[pb_ + 4] & votes[pb_ + 5] & votes[pb_ + 6] & votes[pb_ + 7];
;             if (all) break;
;         }
.LBB0_783:
	s_or_b64 exec, exec, s[12:13]
	s_cmp_eq_u32 s31, -1
	s_waitcnt lgkmcnt(0)
	s_barrier
	s_cbranch_scc1 .LBB0_771
	s_lshl_b32 s12, s17, 5
	s_add_i32 s12, s12, 0x20040
	s_waitcnt vmcnt(0)
	v_mov_b32_e32 v1, s12
	ds_read_b128 v[2:5], v1
	ds_read_b128 v[6:9], v1 offset:16
	s_add_i32 s31, s31, -1
	s_waitcnt lgkmcnt(0)
	v_and_b32_e32 v2, v3, v2
	v_and_b32_e32 v4, v5, v4
	v_and_b32_e32 v6, v7, v6
	v_and_b32_e32 v8, v9, v8
	v_and_b32_e32 v2, v2, v4
	v_and_b32_e32 v6, v6, v8
	v_and_b32_e32 v1, v2, v6
	v_cmp_ne_u32_e64 s[12:13], 0, v1
	s_sub_i32 s34, s34, 64
	s_andn2_b64 vcc, exec, s[12:13]
	s_cbranch_vccnz .LBB0_772
	s_branch .LBB0_657

; template <bool DIFF>
; __device__ __forceinline__ void attn_unit(CA& A, int l, int b, int hh, int qb, LAS unsigned char* lds, float lam, float lam_init) {
;     ...
;         if (key0 <= qlast) {
;             const LAS unsigned char* Kb = lds + AL_KS + buf * AL_KSZ;
;             const LAS unsigned char* Vb = lds + AL_VT + buf * AL_VSZ;
;             f32x16 p[2];
; #pragma unroll
;             for (int kt = 0; kt < 2; ++kt) {
;                 if (!DIFF) {
;                     const LAS float* nc = (const LAS float*)(lds + AL_NC + buf * 512) + 32 * kt + 4 * hi;
; #pragma unroll
;                     for (int g = 0; g < 4; ++g) { const f32x4 c4 = *(const LAS f32x4*)(nc + 8 * g); p[kt][4 * g] = c4[0]; p[kt][4 * g + 1] = c4[1]; p[kt][4 * g + 2] = c4[2]; p[kt][4 * g + 3] = c4[3]; }
;                 }
; #pragma unroll
;                 for (int s = 0; s < NS; ++s) {
;                     const bf16x8 a = *(const LAS bf16x8*)(Kb + (32 * kt + r32) * 144 + (koff + 16 * s + 8 * hi) * 2);
;                     if (DIFF && s == 0) p[kt] = __builtin_amdgcn_mfma_f32_32x32x16_bf16(a, qf[s], negm, 0, 0, 0);
;                     else p[kt] = __builtin_amdgcn_mfma_f32_32x32x16_bf16(a, qf[s], p[kt], 0, 0, 0);
;                 }
;             }
;             if (!DIFF) {
; #pragma unroll
;                 for (int kt = 0; kt < 2; ++kt)
; #pragma unroll
;                     for (int r = 0; r < 16; ++r) p[kt][r] -= m_ref;
;             }
;             if (key0 + 63 > qfirst) {
; #pragma unroll
;                 for (int kt = 0; kt < 2; ++kt)
; #pragma unroll
;                     for (int r = 0; r < 16; ++r) if (key0 + 32 * kt + crow(r, hi) > qmine) p[kt][r] = -1e30f;
;             }
;             first = false;
; #pragma unroll
;             for (int kt = 0; kt < 2; ++kt)
; #pragma unroll
;                 for (int r = 0; r < 16; ++r) p[kt][r] = __builtin_amdgcn_exp2f(p[kt][r]);
;             bf16x8 pb[2][2];
; #pragma unroll
;             for (int kt = 0; kt < 2; ++kt)
; #pragma unroll
;                 for (int i = 0; i < 2; ++i) { v4u w;
; #pragma unroll
;                     for (int j = 0; j < 4; ++j) w[j] = pk2(p[kt][8 * i + 2 * j], p[kt][8 * i + 2 * j + 1]);
;                     pb[kt][i] = __builtin_bit_cast(bf16x8, w); }
; #pragma unroll
;             for (int kt = 0; kt < 2; ++kt)
; #pragma unroll
;                 for (int i = 0; i < 2; ++i) {
; #pragma unroll
.LBB0_786:
	s_mul_i32 s14, s17, 0x2400
	v_add3_u32 v15, v145, s14, v147
	v_lshl_add_u32 v14, s17, 9, v145
	ds_read_b128 v[2:5], v15
	ds_read_b128 v[80:83], v14 offset:35840
	ds_read_b128 v[84:87], v14 offset:35872
	ds_read_b128 v[88:91], v14 offset:35904
	ds_read_b128 v[92:95], v14 offset:35936
	ds_read_b128 v[6:9], v15 offset:32
	s_cmp_le_i32 s34, s26
	s_waitcnt lgkmcnt(1)
	v_mfma_f32_32x32x16_bf16 v[80:95], v[2:5], v[96:99], v[80:95]
	s_waitcnt lgkmcnt(0)
	v_mfma_f32_32x32x16_bf16 v[80:95], v[6:9], v[100:103], v[80:95]
	ds_read_b128 v[2:5], v15 offset:64
	ds_read_b128 v[6:9], v15 offset:4608
	ds_read_b128 v[10:13], v15 offset:96
	s_waitcnt lgkmcnt(2)
	v_mfma_f32_32x32x16_bf16 v[80:95], v[2:5], v[104:107], v[80:95]
	ds_read_b128 v[64:67], v14 offset:35968
	ds_read_b128 v[68:71], v14 offset:36000
	ds_read_b128 v[72:75], v14 offset:36032
	ds_read_b128 v[76:79], v14 offset:36064
	ds_read_b128 v[2:5], v15 offset:4640
	s_waitcnt lgkmcnt(1)
	v_mfma_f32_32x32x16_bf16 v[64:79], v[6:9], v[96:99], v[64:79]
	ds_read_b128 v[6:9], v15 offset:4672
	ds_read_b128 v[150:153], v15 offset:4704
	s_waitcnt lgkmcnt(2)
	v_mfma_f32_32x32x16_bf16 v[64:79], v[2:5], v[100:103], v[64:79]
	s_waitcnt lgkmcnt(1)
	v_mfma_f32_32x32x16_bf16 v[64:79], v[6:9], v[104:107], v[64:79]
	v_mfma_f32_32x32x16_bf16 v[80:95], v[10:13], v[108:111], v[80:95]
	s_waitcnt lgkmcnt(0)
	v_mfma_f32_32x32x16_bf16 v[64:79], v[150:153], v[108:111], v[64:79]
	s_cbranch_scc0 .Lmy_fox_masked
	s_mul_i32 s14, s17, 0x2200
	v_add3_u32 v14, v144, s14, v148
	v_add_u32_e32 v15, 0x5800, v14
	v_add_u32_e32 v14, 0x4800, v14
	ds_read2_b64 v[164:167], v14 offset0:0 offset1:2
	ds_read2_b64 v[168:171], v15 offset0:32 offset1:34
	ds_read2_b64 v[172:175], v14 offset0:4 offset1:6
	ds_read2_b64 v[180:183], v15 offset0:36 offset1:38
	ds_read2_b64 v[184:187], v14 offset0:8 offset1:10
	ds_read2_b64 v[188:191], v15 offset0:40 offset1:42
	ds_read2_b64 v[192:195], v14 offset0:12 offset1:14
	ds_read2_b64 v[196:199], v15 offset0:44 offset1:46
	v_pk_add_f32 v[80:81], v[80:81], v[126:127] neg_lo:[0,1] neg_hi:[0,1]
	v_pk_add_f32 v[82:83], v[82:83], v[126:127] neg_lo:[0,1] neg_hi:[0,1]
	v_pk_add_f32 v[84:85], v[84:85], v[126:127] neg_lo:[0,1] neg_hi:[0,1]
	v_pk_add_f32 v[86:87], v[86:87], v[126:127] neg_lo:[0,1] neg_hi:[0,1]
	v_pk_add_f32 v[88:89], v[88:89], v[126:127] neg_lo:[0,1] neg_hi:[0,1]
	v_pk_add_f32 v[90:91], v[90:91], v[126:127] neg_lo:[0,1] neg_hi:[0,1]
	v_pk_add_f32 v[92:93], v[92:93], v[126:127] neg_lo:[0,1] neg_hi:[0,1]
	v_pk_add_f32 v[94:95], v[94:95], v[126:127] neg_lo:[0,1] neg_hi:[0,1]
	v_pk_add_f32 v[64:65], v[64:65], v[126:127] neg_lo:[0,1] neg_hi:[0,1]
	v_pk_add_f32 v[66:67], v[66:67], v[126:127] neg_lo:[0,1] neg_hi:[0,1]
	v_pk_add_f32 v[68:69], v[68:69], v[126:127] neg_lo:[0,1] neg_hi:[0,1]
	v_pk_add_f32 v[70:71], v[70:71], v[126:127] neg_lo:[0,1] neg_hi:[0,1]
	v_pk_add_f32 v[72:73], v[72:73], v[126:127] neg_lo:[0,1] neg_hi:[0,1]
	v_pk_add_f32 v[74:75], v[74:75], v[126:127] neg_lo:[0,1] neg_hi:[0,1]
	v_pk_add_f32 v[76:77], v[76:77], v[126:127] neg_lo:[0,1] neg_hi:[0,1]
	v_pk_add_f32 v[78:79], v[78:79], v[126:127] neg_lo:[0,1] neg_hi:[0,1]
	v_exp_f32_e32 v80, v80
	v_exp_f32_e32 v81, v81
	v_exp_f32_e32 v82, v82
	v_exp_f32_e32 v83, v83
	v_exp_f32_e32 v84, v84
	v_exp_f32_e32 v85, v85
	v_exp_f32_e32 v86, v86
	v_exp_f32_e32 v87, v87
	v_cvt_pk_bf16_f32 v80, v80, v81
	v_cvt_pk_bf16_f32 v81, v82, v83
	v_cvt_pk_bf16_f32 v82, v84, v85
	v_cvt_pk_bf16_f32 v83, v86, v87
	v_exp_f32_e32 v88, v88
	v_exp_f32_e32 v89, v89
	s_waitcnt lgkmcnt(6)
	v_mfma_f32_32x32x16_bf16 v[32:47], v[164:167], v[80:83], v[32:47]
	v_exp_f32_e32 v90, v90
	v_exp_f32_e32 v91, v91
	v_cvt_pk_bf16_f32 v84, v88, v89
	v_mfma_f32_32x32x16_bf16 v[16:31], v[168:171], v[80:83], v[16:31]
	v_exp_f32_e32 v92, v92
	v_exp_f32_e32 v93, v93
	v_cvt_pk_bf16_f32 v85, v90, v91
	v_mfma_f32_32x32x16_bf16 v[48:63], v[204:207], v[80:83], v[48:63]
	v_exp_f32_e32 v94, v94
	v_exp_f32_e32 v95, v95
	v_cvt_pk_bf16_f32 v86, v92, v93
	v_exp_f32_e32 v64, v64
	v_cvt_pk_bf16_f32 v87, v94, v95
	v_exp_f32_e32 v65, v65
	s_waitcnt lgkmcnt(4)
	v_mfma_f32_32x32x16_bf16 v[32:47], v[172:175], v[84:87], v[32:47]
	v_exp_f32_e32 v66, v66
	v_exp_f32_e32 v67, v67
	v_cvt_pk_bf16_f32 v64, v64, v65
	v_mfma_f32_32x32x16_bf16 v[16:31], v[180:183], v[84:87], v[16:31]
	v_exp_f32_e32 v68, v68
	v_exp_f32_e32 v69, v69
	v_cvt_pk_bf16_f32 v65, v66, v67
	v_mfma_f32_32x32x16_bf16 v[48:63], v[204:207], v[84:87], v[48:63]
	v_exp_f32_e32 v70, v70
	v_exp_f32_e32 v71, v71
	v_cvt_pk_bf16_f32 v66, v68, v69
	v_exp_f32_e32 v72, v72
	v_cvt_pk_bf16_f32 v67, v70, v71
	v_exp_f32_e32 v73, v73
	s_waitcnt lgkmcnt(2)
	v_mfma_f32_32x32x16_bf16 v[32:47], v[184:187], v[64:67], v[32:47]
	v_exp_f32_e32 v74, v74
	v_exp_f32_e32 v75, v75
	v_cvt_pk_bf16_f32 v68, v72, v73
	v_mfma_f32_32x32x16_bf16 v[16:31], v[188:191], v[64:67], v[16:31]
	v_exp_f32_e32 v76, v76
	v_exp_f32_e32 v77, v77
	v_cvt_pk_bf16_f32 v69, v74, v75
	v_mfma_f32_32x32x16_bf16 v[48:63], v[204:207], v[64:67], v[48:63]
	v_exp_f32_e32 v78, v78
	v_exp_f32_e32 v79, v79
	v_cvt_pk_bf16_f32 v70, v76, v77
	s_nop 0
	v_cvt_pk_bf16_f32 v71, v78, v79
	s_waitcnt lgkmcnt(0)
	s_nop 0
	v_mfma_f32_32x32x16_bf16 v[32:47], v[192:195], v[68:71], v[32:47]
	v_mfma_f32_32x32x16_bf16 v[16:31], v[196:199], v[68:71], v[16:31]
	v_mfma_f32_32x32x16_bf16 v[48:63], v[204:207], v[68:71], v[48:63]
	s_mov_b64 s[14:15], 0
	s_branch .Lmy_fox_join
